# step-11 gate-side conv_w x3: first-tile loads of calls 2 and 3 issued up front next to call 1 (renamed address code), their sites use register moves
# baseline (speedup 1.0000x reference)
; #define LAUNDER_V(x) asm volatile("" : "+v"(x))
; #define LAUNDER_S(x) asm volatile("" : "+s"(x))
;     ...
;     int tid = threadIdx.x; LAUNDER_V(tid); int bid = blockIdx.x; LAUNDER_S(bid);
;     const int nkt = K / 64, ntiles = (Ntot / 128) * nkt;
;     float v[16];
;     ...
;     const int cstride = nwg ? nwg : (int)gridDim.x; bid -= wg0;
;     if (bid < 0) return;
;     if (bid < ntiles) CONVW_LOAD(bid);
; __global__ void __launch_bounds__(512, 2) fwd_mega(Params p) {
;     ...
;                 conv_w(p.in[15] + (unsigned)l * 1024 * 1024, 1024, 0, 1024, 1024, 1024, Wa, -1, lds, 128, G - 128);
;                 conv_w(p.in[16] + (unsigned)l * 768 * 1024, 1024, 0, 1024, 1024, 768, Wb, -1, lds, 128, G - 128);
;                 conv_w(p.in[17] + (unsigned)l * 1024 * 1024, 1024, 0, 1024, 1024, 1024, Wo, -1, lds, 128, G - 128);
.LBB0_227:
	v_readlane_b32 s0, v255, 16
	v_readlane_b32 s1, v255, 17
	s_and_b64 s[0:1], s[0:1], exec
	v_mov_b32_e32 v18, v192
	s_mov_b32 s4, s52
	s_cselect_b32 s3, 0x100000, 0
	s_and_b32 s0, s4, 0xffffff80
	s_cmpk_lg_i32 s0, 0x80
	s_cbranch_scc1 .LBB0_232
	v_mov_b32_e32 v222, v192
	s_mov_b32 s64, s52
	s_and_b32 s60, s64, 0xffffff80
	s_cmpk_lg_i32 s60, 0x80
	s_cbranch_scc1 .Lh3_skip
	v_readlane_b32 s66, v253, 0
	s_lshl_b32 s60, s3, 2
	v_readlane_b32 s68, v253, 2
	v_readlane_b32 s67, v253, 1
	v_readlane_b32 s69, v253, 3
	s_add_u32 s60, s68, s60
	s_addc_u32 s61, s69, 0
	s_add_i32 s67, s64, 0xffffff80
	s_lshl_b32 s62, s67, 3
	s_and_b32 s62, s62, 0x380
	v_and_b32_e32 v224, 0x7f, v222
	s_lshl_b32 s64, s64, 6
	v_or_b32_e32 v204, s62, v224
	s_and_b32 s64, s64, 0x3c0
	v_lshlrev_b32_e32 v32, 2, v204
	v_ashrrev_i32_e32 v223, 7, v222
	v_add_u32_e32 v226, 0x200, v222
	v_lshl_add_u64 v[220:221], s[60:61], 0, v[32:33]
	v_add_lshl_u32 v32, s64, v223, 10
	v_ashrrev_i32_e32 v247, 7, v226
	v_add_u32_e32 v227, 0x400, v222
	v_lshl_add_u64 v[204:205], v[32:33], 2, v[220:221]
	v_add_lshl_u32 v32, s64, v247, 10
	v_ashrrev_i32_e32 v246, 7, v227
	v_add_u32_e32 v228, 0x600, v222
	v_lshl_add_u64 v[206:207], v[32:33], 2, v[220:221]
	v_add_lshl_u32 v32, s64, v246, 10
	v_ashrrev_i32_e32 v245, 7, v228
	v_add_u32_e32 v229, 0x800, v222
	global_load_dword v144, v[204:205], off
	v_ashrrev_i32_e32 v244, 7, v229
	global_load_dword v145, v[206:207], off
	v_lshl_add_u64 v[206:207], v[32:33], 2, v[220:221]
	v_add_lshl_u32 v32, s64, v245, 10
	v_add_u32_e32 v230, 0xa00, v222
	v_lshl_add_u64 v[208:209], v[32:33], 2, v[220:221]
	v_add_lshl_u32 v32, s64, v244, 10
	v_ashrrev_i32_e32 v243, 7, v230
	v_add_u32_e32 v231, 0xc00, v222
	global_load_dword v146, v[206:207], off
	v_ashrrev_i32_e32 v242, 7, v231
	global_load_dword v147, v[208:209], off
	v_lshl_add_u64 v[208:209], v[32:33], 2, v[220:221]
	v_add_lshl_u32 v32, s64, v243, 10
	v_add_u32_e32 v232, 0xe00, v222
	v_lshl_add_u64 v[210:211], v[32:33], 2, v[220:221]
	v_add_lshl_u32 v32, s64, v242, 10
	v_ashrrev_i32_e32 v241, 7, v232
	global_load_dword v148, v[208:209], off
	v_lshl_add_u32 v248, v224, 2, 0
	global_load_dword v149, v[210:211], off
	v_lshl_add_u64 v[210:211], v[32:33], 2, v[220:221]
	v_add_lshl_u32 v32, s64, v241, 10
	v_lshl_add_u64 v[212:213], v[32:33], 2, v[220:221]
	global_load_dword v150, v[210:211], off
	v_ashrrev_i32_e32 v225, 5, v222
	global_load_dword v151, v[212:213], off
	v_add_u32_e32 v212, 0x1000, v222
	v_ashrrev_i32_e32 v240, 7, v212
	v_add_lshl_u32 v32, s64, v240, 10
	v_lshl_add_u64 v[212:213], v[32:33], 2, v[220:221]
	global_load_dword v152, v[212:213], off
	v_add_u32_e32 v213, 0x1200, v222
	v_ashrrev_i32_e32 v239, 7, v213
	v_add_lshl_u32 v32, s64, v239, 10
	v_lshl_add_u64 v[214:215], v[32:33], 2, v[220:221]
	global_load_dword v153, v[214:215], off
	v_add_u32_e32 v214, 0x1400, v222
	v_ashrrev_i32_e32 v238, 7, v214
	v_add_lshl_u32 v32, s64, v238, 10
	v_lshl_add_u64 v[214:215], v[32:33], 2, v[220:221]
	global_load_dword v154, v[214:215], off
	v_add_u32_e32 v215, 0x1600, v222
	v_ashrrev_i32_e32 v237, 7, v215
	v_add_lshl_u32 v32, s64, v237, 10
	v_lshl_add_u64 v[216:217], v[32:33], 2, v[220:221]
	global_load_dword v155, v[216:217], off
	v_add_u32_e32 v216, 0x1800, v222
	v_ashrrev_i32_e32 v236, 7, v216
	v_add_lshl_u32 v32, s64, v236, 10
	v_lshl_add_u64 v[216:217], v[32:33], 2, v[220:221]
	global_load_dword v172, v[216:217], off
	v_add_u32_e32 v217, 0x1a00, v222
	v_ashrrev_i32_e32 v235, 7, v217
	v_add_lshl_u32 v32, s64, v235, 10
	v_lshl_add_u64 v[218:219], v[32:33], 2, v[220:221]
	global_load_dword v173, v[218:219], off
	v_add_u32_e32 v218, 0x1c00, v222
	v_ashrrev_i32_e32 v234, 7, v218
	v_add_lshl_u32 v32, s64, v234, 10
	v_lshl_add_u64 v[218:219], v[32:33], 2, v[220:221]
	global_load_dword v174, v[218:219], off
	v_add_u32_e32 v219, 0x1e00, v222
	v_ashrrev_i32_e32 v233, 7, v219
	v_add_lshl_u32 v32, s64, v233, 10
	v_lshl_add_u64 v[220:221], v[32:33], 2, v[220:221]
	global_load_dword v175, v[220:221], off
.Lh3_skip:
	v_mov_b32_e32 v222, v192
	s_mov_b32 s60, s52
	s_add_i32 s68, s60, 0xffffff80
	s_cmpk_gt_u32 s68, 0x5f
	s_cbranch_scc1 .Lh2_skip
	v_readlane_b32 s60, v255, 16
	v_readlane_b32 s61, v255, 17
	s_and_b64 s[60:61], s[60:61], exec
	s_cselect_b32 s60, 0x300000, 0
	v_readlane_b32 s74, v253, 0
	v_readlane_b32 s75, v253, 1
	s_add_u32 s60, s74, s60
	s_addc_u32 s61, s75, 0
	s_and_b32 s64, s68, 0xff
	s_mulk_i32 s64, 0xab
	s_lshr_b32 s64, s64, 11
	s_mul_i32 s65, s64, 12
	s_sub_i32 s65, s68, s65
	v_and_b32_e32 v224, 0x7f, v222
	s_and_b32 s65, s65, 0xff
	v_lshlrev_b32_e32 v223, 2, v224
	s_lshl_b32 s65, s65, 6
	v_lshl_or_b32 v32, s64, 9, v223
	v_ashrrev_i32_e32 v249, 7, v222
	v_add_u32_e32 v226, 0x200, v222
	v_lshl_add_u64 v[220:221], s[60:61], 0, v[32:33]
	v_add_lshl_u32 v32, s65, v249, 10
	v_ashrrev_i32_e32 v247, 7, v226
	v_add_u32_e32 v227, 0x400, v222
	v_lshl_add_u64 v[204:205], v[32:33], 2, v[220:221]
	v_add_lshl_u32 v32, s65, v247, 10
	v_ashrrev_i32_e32 v246, 7, v227
	v_add_u32_e32 v228, 0x600, v222
	v_lshl_add_u64 v[206:207], v[32:33], 2, v[220:221]
	v_add_lshl_u32 v32, s65, v246, 10
	v_ashrrev_i32_e32 v245, 7, v228
	v_add_u32_e32 v229, 0x800, v222
	global_load_dword v128, v[204:205], off
	v_ashrrev_i32_e32 v244, 7, v229
	global_load_dword v129, v[206:207], off
	v_lshl_add_u64 v[206:207], v[32:33], 2, v[220:221]
	v_add_lshl_u32 v32, s65, v245, 10
	v_add_u32_e32 v230, 0xa00, v222
	v_lshl_add_u64 v[208:209], v[32:33], 2, v[220:221]
	v_add_lshl_u32 v32, s65, v244, 10
	v_ashrrev_i32_e32 v243, 7, v230
	v_add_u32_e32 v231, 0xc00, v222
	global_load_dword v130, v[206:207], off
	v_ashrrev_i32_e32 v242, 7, v231
;     ...
;     const int nkt = K / 64, ntiles = (Ntot / 128) * nkt;
;     float v[16];
;     ...
;     const int cstride = nwg ? nwg : (int)gridDim.x; bid -= wg0;
;     if (bid < 0) return;
;     if (bid < ntiles) CONVW_LOAD(bid);
; __global__ void __launch_bounds__(512, 2) fwd_mega(Params p) {
;     ...
;                 conv_w(p.in[16] + (unsigned)l * 768 * 1024, 1024, 0, 1024, 1024, 768, Wb, -1, lds, 128, G - 128);
	global_load_dword v131, v[208:209], off
	v_lshl_add_u64 v[208:209], v[32:33], 2, v[220:221]
	v_add_lshl_u32 v32, s65, v243, 10
	v_add_u32_e32 v232, 0xe00, v222
	v_lshl_add_u64 v[210:211], v[32:33], 2, v[220:221]
	v_add_lshl_u32 v32, s65, v242, 10
	v_ashrrev_i32_e32 v241, 7, v232
	global_load_dword v132, v[208:209], off
	v_add_u32_e32 v223, 0, v223
	global_load_dword v133, v[210:211], off
	v_lshl_add_u64 v[210:211], v[32:33], 2, v[220:221]
	v_add_lshl_u32 v32, s65, v241, 10
	v_lshl_add_u64 v[212:213], v[32:33], 2, v[220:221]
	global_load_dword v134, v[210:211], off
	v_ashrrev_i32_e32 v225, 5, v222
	global_load_dword v135, v[212:213], off
	v_add_u32_e32 v212, 0x1000, v222
	v_ashrrev_i32_e32 v240, 7, v212
	v_add_lshl_u32 v32, s65, v240, 10
	v_lshl_add_u64 v[212:213], v[32:33], 2, v[220:221]
	global_load_dword v136, v[212:213], off
	v_add_u32_e32 v213, 0x1200, v222
	v_ashrrev_i32_e32 v239, 7, v213
	v_add_lshl_u32 v32, s65, v239, 10
	v_lshl_add_u64 v[214:215], v[32:33], 2, v[220:221]
	global_load_dword v137, v[214:215], off
	v_add_u32_e32 v214, 0x1400, v222
	v_ashrrev_i32_e32 v238, 7, v214
	v_add_lshl_u32 v32, s65, v238, 10
	v_lshl_add_u64 v[214:215], v[32:33], 2, v[220:221]
	global_load_dword v138, v[214:215], off
	v_add_u32_e32 v215, 0x1600, v222
	v_ashrrev_i32_e32 v237, 7, v215
	v_add_lshl_u32 v32, s65, v237, 10
	v_lshl_add_u64 v[216:217], v[32:33], 2, v[220:221]
	global_load_dword v139, v[216:217], off
	v_add_u32_e32 v216, 0x1800, v222
	v_ashrrev_i32_e32 v236, 7, v216
	v_add_lshl_u32 v32, s65, v236, 10
	v_lshl_add_u64 v[216:217], v[32:33], 2, v[220:221]
	global_load_dword v140, v[216:217], off
	v_add_u32_e32 v217, 0x1a00, v222
	v_ashrrev_i32_e32 v235, 7, v217
	v_add_lshl_u32 v32, s65, v235, 10
	v_lshl_add_u64 v[218:219], v[32:33], 2, v[220:221]
	global_load_dword v141, v[218:219], off
	v_add_u32_e32 v218, 0x1c00, v222
	v_ashrrev_i32_e32 v234, 7, v218
	v_add_lshl_u32 v32, s65, v234, 10
	v_lshl_add_u64 v[218:219], v[32:33], 2, v[220:221]
	global_load_dword v142, v[218:219], off
	v_add_u32_e32 v219, 0x1e00, v222
	v_ashrrev_i32_e32 v233, 7, v219
	v_add_lshl_u32 v32, s65, v233, 10
	v_lshl_add_u64 v[220:221], v[32:33], 2, v[220:221]
	global_load_dword v143, v[220:221], off
; #define LDS_BARRIER() do { asm volatile("s_waitcnt lgkmcnt(0)" ::: "memory"); __builtin_amdgcn_s_barrier(); asm volatile("" ::: "memory"); } while (0)
; #define LAUNDER_V(x) asm volatile("" : "+v"(x))
; #define LAUNDER_S(x) asm volatile("" : "+s"(x))
;     ...
;     int tid = threadIdx.x; LAUNDER_V(tid); int bid = blockIdx.x; LAUNDER_S(bid);
;     const int nkt = K / 64, ntiles = (Ntot / 128) * nkt;
;     float v[16];
;     ...
;     const int cstride = nwg ? nwg : (int)gridDim.x; bid -= wg0;
;     if (bid < 0) return;
;     if (bid < ntiles) CONVW_LOAD(bid);
;     for (int t = bid; t < ntiles; t += cstride) {
;         const int n0 = (t / nkt) * 128, k0 = (t % nkt) * 64;
; #pragma unroll
;         for (int it = 0; it < 16; ++it) { const int e = tid + 512 * it, kk = e >> 7, nn = e & 127; tile[kk * 129 + nn] = v[it]; }
;         LDS_BARRIER();
;         if (t + cstride < ntiles) CONVW_LOAD(t + cstride);
; #pragma unroll
;         for (int it = 0; it < 8; ++it) {
;             const int e = tid + 512 * it, nn = e >> 5, kp = e & 31, n = n0 + nn;
;             const int dr = (inter >= 0) ? ((n >> 7) * 256 + inter * 128 + (n & 127)) : n;
;             h16x2 o; o[0] = (h16)tile[(2 * kp) * 129 + nn]; o[1] = (h16)tile[(2 * kp + 1) * 129 + nn];
;             gst((h16x2*)(dst + (unsigned)dr * K + k0 + 2 * kp), o);
.Lh2_skip:
	v_readlane_b32 s8, v253, 34
	s_lshl_b32 s0, s3, 2
	v_readlane_b32 s22, v253, 48
	v_readlane_b32 s10, v253, 36
	v_readlane_b32 s23, v253, 49
	s_add_u32 s0, s22, s0
	s_addc_u32 s1, s23, 0
	s_add_i32 s10, s4, 0xffffff80
	s_lshl_b32 s5, s10, 3
	s_and_b32 s5, s5, 0x380
	v_and_b32_e32 v20, 0x7f, v18
	s_lshl_b32 s4, s4, 6
	v_or_b32_e32 v0, s5, v20
	s_and_b32 s4, s4, 0x3c0
	v_lshlrev_b32_e32 v32, 2, v0
	v_ashrrev_i32_e32 v19, 7, v18
	v_add_u32_e32 v23, 0x200, v18
	v_lshl_add_u64 v[16:17], s[0:1], 0, v[32:33]
	v_add_lshl_u32 v32, s4, v19, 10
	v_ashrrev_i32_e32 v53, 7, v23
	v_add_u32_e32 v25, 0x400, v18
	v_lshl_add_u64 v[0:1], v[32:33], 2, v[16:17]
	v_add_lshl_u32 v32, s4, v53, 10
	v_ashrrev_i32_e32 v52, 7, v25
	v_add_u32_e32 v27, 0x600, v18
	v_lshl_add_u64 v[2:3], v[32:33], 2, v[16:17]
	v_add_lshl_u32 v32, s4, v52, 10
	v_ashrrev_i32_e32 v51, 7, v27
	v_add_u32_e32 v29, 0x800, v18
	global_load_dword v0, v[0:1], off
	v_ashrrev_i32_e32 v50, 7, v29
	global_load_dword v1, v[2:3], off
	v_lshl_add_u64 v[2:3], v[32:33], 2, v[16:17]
	v_add_lshl_u32 v32, s4, v51, 10
	v_add_u32_e32 v31, 0xa00, v18
	v_lshl_add_u64 v[4:5], v[32:33], 2, v[16:17]
	v_add_lshl_u32 v32, s4, v50, 10
	v_ashrrev_i32_e32 v49, 7, v31
	v_add_u32_e32 v35, 0xc00, v18
	global_load_dword v2, v[2:3], off
	v_ashrrev_i32_e32 v48, 7, v35
	global_load_dword v3, v[4:5], off
	v_lshl_add_u64 v[4:5], v[32:33], 2, v[16:17]
	v_add_lshl_u32 v32, s4, v49, 10
	v_add_u32_e32 v37, 0xe00, v18
	v_lshl_add_u64 v[6:7], v[32:33], 2, v[16:17]
	v_add_lshl_u32 v32, s4, v48, 10
	v_ashrrev_i32_e32 v47, 7, v37
	global_load_dword v4, v[4:5], off
	v_readlane_b32 s9, v253, 35
	global_load_dword v5, v[6:7], off
	v_lshl_add_u64 v[6:7], v[32:33], 2, v[16:17]
	v_add_lshl_u32 v32, s4, v47, 10
	v_lshl_add_u64 v[8:9], v[32:33], 2, v[16:17]
	global_load_dword v6, v[6:7], off
	v_lshl_add_u32 v70, v20, 2, 0
	global_load_dword v7, v[8:9], off
	v_add_u32_e32 v8, 0x1000, v18
	v_ashrrev_i32_e32 v46, 7, v8
	v_add_lshl_u32 v32, s4, v46, 10
	v_lshl_add_u64 v[8:9], v[32:33], 2, v[16:17]
	global_load_dword v8, v[8:9], off
	v_add_u32_e32 v9, 0x1200, v18
	v_ashrrev_i32_e32 v45, 7, v9
	v_add_lshl_u32 v32, s4, v45, 10
	v_lshl_add_u64 v[10:11], v[32:33], 2, v[16:17]
	global_load_dword v9, v[10:11], off
	v_add_u32_e32 v10, 0x1400, v18
	v_ashrrev_i32_e32 v44, 7, v10
	v_add_lshl_u32 v32, s4, v44, 10
	v_lshl_add_u64 v[10:11], v[32:33], 2, v[16:17]
	global_load_dword v10, v[10:11], off
	v_add_u32_e32 v11, 0x1600, v18
	v_ashrrev_i32_e32 v43, 7, v11
	v_add_lshl_u32 v32, s4, v43, 10
	v_lshl_add_u64 v[12:13], v[32:33], 2, v[16:17]
	global_load_dword v11, v[12:13], off
	v_add_u32_e32 v12, 0x1800, v18
	v_ashrrev_i32_e32 v42, 7, v12
	v_add_lshl_u32 v32, s4, v42, 10
	v_lshl_add_u64 v[12:13], v[32:33], 2, v[16:17]
	global_load_dword v12, v[12:13], off
	v_add_u32_e32 v13, 0x1a00, v18
	v_ashrrev_i32_e32 v41, 7, v13
	v_add_lshl_u32 v32, s4, v41, 10
	v_lshl_add_u64 v[14:15], v[32:33], 2, v[16:17]
	global_load_dword v13, v[14:15], off
	v_add_u32_e32 v14, 0x1c00, v18
	v_ashrrev_i32_e32 v40, 7, v14
	v_add_lshl_u32 v32, s4, v40, 10
	v_lshl_add_u64 v[14:15], v[32:33], 2, v[16:17]
	global_load_dword v14, v[14:15], off
	v_add_u32_e32 v15, 0x1e00, v18
	v_ashrrev_i32_e32 v39, 7, v15
	v_add_lshl_u32 v32, s4, v39, 10
	v_lshl_add_u64 v[16:17], v[32:33], 2, v[16:17]
	global_load_dword v15, v[16:17], off
	v_lshlrev_b32_e32 v16, 1, v18
	v_and_b32_e32 v16, 62, v16
	v_readlane_b32 s4, v255, 7
	v_lshlrev_b32_e32 v32, 1, v16
	v_readlane_b32 s5, v255, 8
	v_mad_u32_u24 v38, v16, s82, 0
	v_ashrrev_i32_e32 v21, 5, v18
	v_lshl_add_u64 v[16:17], s[4:5], 0, v[32:33]
	v_readlane_b32 s5, v253, 56
	v_mul_lo_u32 v18, v19, s82
	v_mul_lo_u32 v32, v53, s82
	v_mul_lo_u32 v57, v52, s82
	v_mul_lo_u32 v58, v51, s82
	v_mul_lo_u32 v59, v50, s82
	v_mul_lo_u32 v60, v49, s82
	v_mul_lo_u32 v61, v48, s82
	v_mul_lo_u32 v62, v47, s82
	v_mul_lo_u32 v63, v46, s82
	v_mul_lo_u32 v64, v45, s82
	v_mul_lo_u32 v65, v44, s82
	v_mul_lo_u32 v66, v43, s82
	v_mul_lo_u32 v67, v42, s82
	v_mul_lo_u32 v68, v41, s82
	v_mul_lo_u32 v69, v40, s82
	v_mul_lo_u32 v71, v39, s82
	v_ashrrev_i32_e32 v23, 5, v23
	v_ashrrev_i32_e32 v25, 5, v25
	v_ashrrev_i32_e32 v27, 5, v27
	v_ashrrev_i32_e32 v29, 5, v29
	v_ashrrev_i32_e32 v31, 5, v31
	v_ashrrev_i32_e32 v35, 5, v35
	v_ashrrev_i32_e32 v37, 5, v37
	s_add_i32 s4, s5, s10
	v_lshl_add_u32 v22, v21, 2, v38
	v_lshl_add_u32 v24, v23, 2, v38
	v_lshl_add_u32 v26, v25, 2, v38
	v_lshl_add_u32 v28, v27, 2, v38
	v_lshl_add_u32 v30, v29, 2, v38
	v_lshl_add_u32 v34, v31, 2, v38
	v_lshl_add_u32 v36, v35, 2, v38
	v_lshl_add_u32 v38, v37, 2, v38
	s_lshl_b32 s6, s10, 6
	s_lshl_b32 s7, s5, 6
	v_lshlrev_b32_e32 v39, 10, v39
	s_lshl_b32 s8, s4, 16
	s_lshl_b32 s9, s5, 16
	v_lshlrev_b32_e32 v40, 10, v40
	v_lshlrev_b32_e32 v41, 10, v41
	v_lshlrev_b32_e32 v42, 10, v42
	v_lshlrev_b32_e32 v43, 10, v43
	v_lshlrev_b32_e32 v44, 10, v44
	v_lshlrev_b32_e32 v45, 10, v45
	v_lshlrev_b32_e32 v46, 10, v46
	v_lshlrev_b32_e32 v47, 10, v47
	v_lshlrev_b32_e32 v48, 10, v48
	v_lshlrev_b32_e32 v49, 10, v49
	v_lshlrev_b32_e32 v50, 10, v50
	v_lshlrev_b32_e32 v51, 10, v51
	v_lshlrev_b32_e32 v52, 10, v52
	v_lshlrev_b32_e32 v53, 10, v53
	v_lshlrev_b32_e32 v54, 10, v19
	v_add_u32_e32 v55, v70, v18
	v_add_u32_e32 v56, v70, v32
	v_add_u32_e32 v57, v70, v57
	v_add_u32_e32 v58, v70, v58
	v_add_u32_e32 v59, v70, v59
	v_add_u32_e32 v60, v70, v60
	v_add_u32_e32 v61, v70, v61
	v_add_u32_e32 v62, v70, v62
	v_add_u32_e32 v63, v70, v63
	v_add_u32_e32 v64, v70, v64
	v_add_u32_e32 v65, v70, v65
	v_add_u32_e32 v66, v70, v66
	v_add_u32_e32 v67, v70, v67
	v_add_u32_e32 v68, v70, v68
	v_add_u32_e32 v69, v70, v69
	v_add_u32_e32 v70, v70, v71
	v_readlane_b32 s11, v253, 37
	v_readlane_b32 s12, v253, 38
	v_readlane_b32 s13, v253, 39
	v_readlane_b32 s14, v253, 40
	v_readlane_b32 s15, v253, 41
	v_readlane_b32 s16, v253, 42
	v_readlane_b32 s17, v253, 43
	v_readlane_b32 s18, v253, 44
	v_readlane_b32 s19, v253, 45
	v_readlane_b32 s20, v253, 46
	v_readlane_b32 s21, v253, 47
	s_branch .LBB0_230

;     ...
;     const int nkt = K / 64, ntiles = (Ntot / 128) * nkt;
;     float v[16];
;     ...
;     const int cstride = nwg ? nwg : (int)gridDim.x; bid -= wg0;
;     if (bid < 0) return;
;     if (bid < ntiles) CONVW_LOAD(bid);
; __global__ void __launch_bounds__(512, 2) fwd_mega(Params p) {
;     ...
;                 conv_w(p.in[16] + (unsigned)l * 768 * 1024, 1024, 0, 1024, 1024, 768, Wb, -1, lds, 128, G - 128);
.LBB0_232:
	v_mov_b32_e32 v18, v192
	s_mov_b32 s0, s52
	s_add_i32 s10, s0, 0xffffff80
	s_cmpk_gt_u32 s10, 0x5f
	s_cbranch_scc1 .LBB0_237
	v_readlane_b32 s0, v255, 16
	v_readlane_b32 s1, v255, 17
	s_and_b64 s[0:1], s[0:1], exec
	s_cselect_b32 s0, 0x300000, 0
	v_readlane_b32 s36, v253, 0
	v_readlane_b32 s37, v253, 1
	s_add_u32 s0, s36, s0
	s_addc_u32 s1, s37, 0
	s_and_b32 s4, s10, 0xff
	s_mulk_i32 s4, 0xab
	s_lshr_b32 s4, s4, 11
	s_mul_i32 s5, s4, 12
	s_sub_i32 s5, s10, s5
	v_and_b32_e32 v20, 0x7f, v18
	s_and_b32 s5, s5, 0xff
	v_lshlrev_b32_e32 v19, 2, v20
	s_lshl_b32 s5, s5, 6
	v_lshl_or_b32 v32, s4, 9, v19
	v_ashrrev_i32_e32 v54, 7, v18
	v_add_u32_e32 v23, 0x200, v18
	v_lshl_add_u64 v[16:17], s[0:1], 0, v[32:33]
	v_add_lshl_u32 v32, s5, v54, 10
	v_ashrrev_i32_e32 v53, 7, v23
	v_add_u32_e32 v25, 0x400, v18
	v_lshl_add_u64 v[0:1], v[32:33], 2, v[16:17]
	v_add_lshl_u32 v32, s5, v53, 10
	v_ashrrev_i32_e32 v52, 7, v25
	v_add_u32_e32 v27, 0x600, v18
	v_lshl_add_u64 v[2:3], v[32:33], 2, v[16:17]
	v_add_lshl_u32 v32, s5, v52, 10
	v_ashrrev_i32_e32 v51, 7, v27
	v_add_u32_e32 v29, 0x800, v18
	v_mov_b32_e32 v0, v128
	v_ashrrev_i32_e32 v50, 7, v29
	v_mov_b32_e32 v1, v129
	v_lshl_add_u64 v[2:3], v[32:33], 2, v[16:17]
	v_add_lshl_u32 v32, s5, v51, 10
	v_add_u32_e32 v31, 0xa00, v18
	v_lshl_add_u64 v[4:5], v[32:33], 2, v[16:17]
	v_add_lshl_u32 v32, s5, v50, 10
	v_ashrrev_i32_e32 v49, 7, v31
	v_add_u32_e32 v35, 0xc00, v18
	v_mov_b32_e32 v2, v130
	v_ashrrev_i32_e32 v48, 7, v35
	v_mov_b32_e32 v3, v131
	v_lshl_add_u64 v[4:5], v[32:33], 2, v[16:17]
	v_add_lshl_u32 v32, s5, v49, 10
	v_add_u32_e32 v37, 0xe00, v18
	v_lshl_add_u64 v[6:7], v[32:33], 2, v[16:17]
	v_add_lshl_u32 v32, s5, v48, 10
	v_ashrrev_i32_e32 v47, 7, v37
	v_mov_b32_e32 v4, v132
	v_add_u32_e32 v19, 0, v19
	v_mov_b32_e32 v5, v133
	v_lshl_add_u64 v[6:7], v[32:33], 2, v[16:17]
	v_add_lshl_u32 v32, s5, v47, 10
	v_lshl_add_u64 v[8:9], v[32:33], 2, v[16:17]
	v_mov_b32_e32 v6, v134
	v_ashrrev_i32_e32 v21, 5, v18
	v_mov_b32_e32 v7, v135
	v_add_u32_e32 v8, 0x1000, v18
	v_ashrrev_i32_e32 v46, 7, v8
	v_add_lshl_u32 v32, s5, v46, 10
	v_lshl_add_u64 v[8:9], v[32:33], 2, v[16:17]
	v_mov_b32_e32 v8, v136
	v_add_u32_e32 v9, 0x1200, v18
	v_ashrrev_i32_e32 v45, 7, v9
	v_add_lshl_u32 v32, s5, v45, 10
	v_lshl_add_u64 v[10:11], v[32:33], 2, v[16:17]
	v_mov_b32_e32 v9, v137
	v_add_u32_e32 v10, 0x1400, v18
	v_ashrrev_i32_e32 v44, 7, v10
	v_add_lshl_u32 v32, s5, v44, 10
	v_lshl_add_u64 v[10:11], v[32:33], 2, v[16:17]
	v_mov_b32_e32 v10, v138
	v_add_u32_e32 v11, 0x1600, v18
	v_ashrrev_i32_e32 v43, 7, v11
	v_add_lshl_u32 v32, s5, v43, 10
	v_lshl_add_u64 v[12:13], v[32:33], 2, v[16:17]
	v_mov_b32_e32 v11, v139
	v_add_u32_e32 v12, 0x1800, v18
	v_ashrrev_i32_e32 v42, 7, v12
	v_add_lshl_u32 v32, s5, v42, 10
	v_lshl_add_u64 v[12:13], v[32:33], 2, v[16:17]
	v_mov_b32_e32 v12, v140
	v_add_u32_e32 v13, 0x1a00, v18
	v_ashrrev_i32_e32 v41, 7, v13
	v_add_lshl_u32 v32, s5, v41, 10
	v_lshl_add_u64 v[14:15], v[32:33], 2, v[16:17]
	v_mov_b32_e32 v13, v141
	v_add_u32_e32 v14, 0x1c00, v18
	v_ashrrev_i32_e32 v40, 7, v14
	v_add_lshl_u32 v32, s5, v40, 10
	v_lshl_add_u64 v[14:15], v[32:33], 2, v[16:17]
	v_mov_b32_e32 v14, v142
	v_add_u32_e32 v15, 0x1e00, v18
	v_ashrrev_i32_e32 v39, 7, v15
	v_add_lshl_u32 v32, s5, v39, 10
	v_lshl_add_u64 v[16:17], v[32:33], 2, v[16:17]
	v_mov_b32_e32 v15, v143
	v_lshlrev_b32_e32 v16, 1, v18
	v_and_b32_e32 v16, 62, v16
	v_readlane_b32 s4, v255, 9
	v_lshlrev_b32_e32 v32, 1, v16
	v_readlane_b32 s5, v255, 10
	v_mad_u32_u24 v38, v16, s82, 0
	v_mul_lo_u32 v18, v54, s82
	v_lshl_add_u64 v[16:17], s[4:5], 0, v[32:33]
	v_readlane_b32 s5, v253, 56
	v_mul_lo_u32 v32, v53, s82
	v_mul_lo_u32 v57, v52, s82
	v_mul_lo_u32 v58, v51, s82
	v_mul_lo_u32 v59, v50, s82
	v_mul_lo_u32 v60, v49, s82
	v_mul_lo_u32 v61, v48, s82
	v_mul_lo_u32 v62, v47, s82
	v_mul_lo_u32 v63, v46, s82
	v_mul_lo_u32 v64, v45, s82
	v_mul_lo_u32 v65, v44, s82
	v_mul_lo_u32 v66, v43, s82
	v_mul_lo_u32 v67, v42, s82
	v_mul_lo_u32 v68, v41, s82
	v_mul_lo_u32 v69, v40, s82
	v_mul_lo_u32 v70, v39, s82
	v_ashrrev_i32_e32 v23, 5, v23
	v_ashrrev_i32_e32 v25, 5, v25
	v_ashrrev_i32_e32 v27, 5, v27
	v_ashrrev_i32_e32 v29, 5, v29
	v_ashrrev_i32_e32 v31, 5, v31
	v_ashrrev_i32_e32 v35, 5, v35
	v_ashrrev_i32_e32 v37, 5, v37
	s_add_i32 s4, s5, s10
	v_lshl_add_u32 v22, v21, 2, v38
	v_lshl_add_u32 v24, v23, 2, v38
	v_lshl_add_u32 v26, v25, 2, v38
	v_lshl_add_u32 v28, v27, 2, v38
	v_lshl_add_u32 v30, v29, 2, v38
	v_lshl_add_u32 v34, v31, 2, v38
	v_lshl_add_u32 v36, v35, 2, v38
	v_lshl_add_u32 v38, v37, 2, v38
	s_lshl_b32 s6, s10, 6
	s_lshl_b32 s7, s5, 6
	v_lshlrev_b32_e32 v39, 10, v39
	s_lshl_b32 s8, s4, 16
	s_lshl_b32 s9, s5, 16
	v_lshlrev_b32_e32 v40, 10, v40
	v_lshlrev_b32_e32 v41, 10, v41
	v_lshlrev_b32_e32 v42, 10, v42
	v_lshlrev_b32_e32 v43, 10, v43
	v_lshlrev_b32_e32 v44, 10, v44
	v_lshlrev_b32_e32 v45, 10, v45
	v_lshlrev_b32_e32 v46, 10, v46
	v_lshlrev_b32_e32 v47, 10, v47
	v_lshlrev_b32_e32 v48, 10, v48
	v_lshlrev_b32_e32 v49, 10, v49
	v_lshlrev_b32_e32 v50, 10, v50
	v_lshlrev_b32_e32 v51, 10, v51
	v_lshlrev_b32_e32 v52, 10, v52
	v_lshlrev_b32_e32 v53, 10, v53
	v_lshlrev_b32_e32 v54, 10, v54
	v_add_u32_e32 v55, v19, v18
	v_add_u32_e32 v56, v19, v32
	v_add_u32_e32 v57, v19, v57
	v_add_u32_e32 v58, v19, v58
	v_add_u32_e32 v59, v19, v59
	v_add_u32_e32 v60, v19, v60
	v_add_u32_e32 v61, v19, v61
	v_add_u32_e32 v62, v19, v62
	v_add_u32_e32 v63, v19, v63
	v_add_u32_e32 v64, v19, v64
	v_add_u32_e32 v65, v19, v65
	v_add_u32_e32 v66, v19, v66
	v_add_u32_e32 v67, v19, v67
	v_add_u32_e32 v68, v19, v68
	v_add_u32_e32 v69, v19, v69
	v_add_u32_e32 v70, v19, v70
	v_readlane_b32 s38, v253, 2
	v_readlane_b32 s39, v253, 3
	v_readlane_b32 s40, v253, 4
	v_readlane_b32 s41, v253, 5
	v_readlane_b32 s42, v253, 6
	v_readlane_b32 s43, v253, 7
	v_readlane_b32 s44, v253, 8
	v_readlane_b32 s45, v253, 9
	v_readlane_b32 s46, v253, 10
	v_readlane_b32 s47, v253, 11
	v_readlane_b32 s48, v253, 12
	v_readlane_b32 s49, v253, 13
	v_readlane_b32 s50, v253, 14
	v_readlane_b32 s51, v253, 15
	s_branch .LBB0_235

;     ...
;     const int nkt = K / 64, ntiles = (Ntot / 128) * nkt;
;     float v[16];
;     ...
;     const int cstride = nwg ? nwg : (int)gridDim.x; bid -= wg0;
;     if (bid < 0) return;
;     if (bid < ntiles) CONVW_LOAD(bid);
; __global__ void __launch_bounds__(512, 2) fwd_mega(Params p) {
;     ...
;                 conv_w(p.in[17] + (unsigned)l * 1024 * 1024, 1024, 0, 1024, 1024, 1024, Wo, -1, lds, 128, G - 128);
.LBB0_237:
	v_mov_b32_e32 v18, v192
	s_mov_b32 s4, s52
	s_and_b32 s0, s4, 0xffffff80
	s_cmpk_lg_i32 s0, 0x80
	s_cbranch_scc1 .LBB0_242
	v_readlane_b32 s8, v253, 0
	s_lshl_b32 s0, s3, 2
	v_readlane_b32 s10, v253, 2
	v_readlane_b32 s9, v253, 1
	v_readlane_b32 s11, v253, 3
	s_add_u32 s0, s10, s0
	s_addc_u32 s1, s11, 0
	s_add_i32 s9, s4, 0xffffff80
	s_lshl_b32 s3, s9, 3
	s_and_b32 s3, s3, 0x380
	v_and_b32_e32 v20, 0x7f, v18
	s_lshl_b32 s4, s4, 6
	v_or_b32_e32 v0, s3, v20
	s_and_b32 s4, s4, 0x3c0
	v_lshlrev_b32_e32 v32, 2, v0
	v_ashrrev_i32_e32 v19, 7, v18
	v_add_u32_e32 v23, 0x200, v18
	v_lshl_add_u64 v[16:17], s[0:1], 0, v[32:33]
	v_add_lshl_u32 v32, s4, v19, 10
	v_ashrrev_i32_e32 v53, 7, v23
	v_add_u32_e32 v25, 0x400, v18
	v_lshl_add_u64 v[0:1], v[32:33], 2, v[16:17]
	v_add_lshl_u32 v32, s4, v53, 10
	v_ashrrev_i32_e32 v52, 7, v25
	v_add_u32_e32 v27, 0x600, v18
	v_lshl_add_u64 v[2:3], v[32:33], 2, v[16:17]
	v_add_lshl_u32 v32, s4, v52, 10
	v_ashrrev_i32_e32 v51, 7, v27
	v_add_u32_e32 v29, 0x800, v18
	v_mov_b32_e32 v0, v144
	v_ashrrev_i32_e32 v50, 7, v29
	v_mov_b32_e32 v1, v145
	v_lshl_add_u64 v[2:3], v[32:33], 2, v[16:17]
	v_add_lshl_u32 v32, s4, v51, 10
	v_add_u32_e32 v31, 0xa00, v18
	v_lshl_add_u64 v[4:5], v[32:33], 2, v[16:17]
	v_add_lshl_u32 v32, s4, v50, 10
	v_ashrrev_i32_e32 v49, 7, v31
	v_add_u32_e32 v35, 0xc00, v18
	v_mov_b32_e32 v2, v146
	v_ashrrev_i32_e32 v48, 7, v35
	v_mov_b32_e32 v3, v147
	v_lshl_add_u64 v[4:5], v[32:33], 2, v[16:17]
	v_add_lshl_u32 v32, s4, v49, 10
	v_add_u32_e32 v37, 0xe00, v18
	v_lshl_add_u64 v[6:7], v[32:33], 2, v[16:17]
	v_add_lshl_u32 v32, s4, v48, 10
	v_ashrrev_i32_e32 v47, 7, v37
	v_mov_b32_e32 v4, v148
	v_lshl_add_u32 v70, v20, 2, 0
	v_mov_b32_e32 v5, v149
	v_lshl_add_u64 v[6:7], v[32:33], 2, v[16:17]
	v_add_lshl_u32 v32, s4, v47, 10
	v_lshl_add_u64 v[8:9], v[32:33], 2, v[16:17]
	v_mov_b32_e32 v6, v150
	v_ashrrev_i32_e32 v21, 5, v18
	v_mov_b32_e32 v7, v151
	v_add_u32_e32 v8, 0x1000, v18
	v_ashrrev_i32_e32 v46, 7, v8
	v_add_lshl_u32 v32, s4, v46, 10
	v_lshl_add_u64 v[8:9], v[32:33], 2, v[16:17]
	v_mov_b32_e32 v8, v152
	v_add_u32_e32 v9, 0x1200, v18
	v_ashrrev_i32_e32 v45, 7, v9
	v_add_lshl_u32 v32, s4, v45, 10
	v_lshl_add_u64 v[10:11], v[32:33], 2, v[16:17]
	v_mov_b32_e32 v9, v153
	v_add_u32_e32 v10, 0x1400, v18
	v_ashrrev_i32_e32 v44, 7, v10
	v_add_lshl_u32 v32, s4, v44, 10
	v_lshl_add_u64 v[10:11], v[32:33], 2, v[16:17]
	v_mov_b32_e32 v10, v154
	v_add_u32_e32 v11, 0x1600, v18
	v_ashrrev_i32_e32 v43, 7, v11
	v_add_lshl_u32 v32, s4, v43, 10
	v_lshl_add_u64 v[12:13], v[32:33], 2, v[16:17]
	v_mov_b32_e32 v11, v155
	v_add_u32_e32 v12, 0x1800, v18
	v_ashrrev_i32_e32 v42, 7, v12
	v_add_lshl_u32 v32, s4, v42, 10
	v_lshl_add_u64 v[12:13], v[32:33], 2, v[16:17]
	v_mov_b32_e32 v12, v172
	v_add_u32_e32 v13, 0x1a00, v18
	v_ashrrev_i32_e32 v41, 7, v13
	v_add_lshl_u32 v32, s4, v41, 10
	v_lshl_add_u64 v[14:15], v[32:33], 2, v[16:17]
	v_mov_b32_e32 v13, v173
	v_add_u32_e32 v14, 0x1c00, v18
	v_ashrrev_i32_e32 v40, 7, v14
	v_add_lshl_u32 v32, s4, v40, 10
	v_lshl_add_u64 v[14:15], v[32:33], 2, v[16:17]
	v_mov_b32_e32 v14, v174
	v_add_u32_e32 v15, 0x1e00, v18
	v_ashrrev_i32_e32 v39, 7, v15
	v_add_lshl_u32 v32, s4, v39, 10
	v_lshl_add_u64 v[16:17], v[32:33], 2, v[16:17]
	v_mov_b32_e32 v15, v175
	v_lshlrev_b32_e32 v16, 1, v18
	v_and_b32_e32 v16, 62, v16
	v_readlane_b32 s4, v255, 11
	v_lshlrev_b32_e32 v32, 1, v16
	v_readlane_b32 s5, v255, 12
	v_mad_u32_u24 v38, v16, s82, 0
	v_mul_lo_u32 v18, v19, s82
	v_lshl_add_u64 v[16:17], s[4:5], 0, v[32:33]
	v_readlane_b32 s5, v253, 56
	v_mul_lo_u32 v32, v53, s82
	v_mul_lo_u32 v57, v52, s82
	v_mul_lo_u32 v58, v51, s82
	v_mul_lo_u32 v59, v50, s82
	v_mul_lo_u32 v60, v49, s82
	v_mul_lo_u32 v61, v48, s82
	v_mul_lo_u32 v62, v47, s82
	v_mul_lo_u32 v63, v46, s82
	v_mul_lo_u32 v64, v45, s82
	v_mul_lo_u32 v65, v44, s82
	v_mul_lo_u32 v66, v43, s82
	v_mul_lo_u32 v67, v42, s82
	v_mul_lo_u32 v68, v41, s82
	v_mul_lo_u32 v69, v40, s82
	v_mul_lo_u32 v71, v39, s82
	v_ashrrev_i32_e32 v23, 5, v23
	v_ashrrev_i32_e32 v25, 5, v25
	v_ashrrev_i32_e32 v27, 5, v27
	v_ashrrev_i32_e32 v29, 5, v29
	v_ashrrev_i32_e32 v31, 5, v31
	v_ashrrev_i32_e32 v35, 5, v35
	v_ashrrev_i32_e32 v37, 5, v37
	s_add_i32 s4, s5, s9
	v_lshl_add_u32 v22, v21, 2, v38
	v_lshl_add_u32 v24, v23, 2, v38
	v_lshl_add_u32 v26, v25, 2, v38
	v_lshl_add_u32 v28, v27, 2, v38
	v_lshl_add_u32 v30, v29, 2, v38
	v_lshl_add_u32 v34, v31, 2, v38
	v_lshl_add_u32 v36, v35, 2, v38
	v_lshl_add_u32 v38, v37, 2, v38
	s_lshl_b32 s3, s9, 6
	s_lshl_b32 s6, s5, 6
	v_lshlrev_b32_e32 v39, 10, v39
	s_lshl_b32 s7, s4, 16
	s_lshl_b32 s8, s5, 16
	v_lshlrev_b32_e32 v40, 10, v40
	v_lshlrev_b32_e32 v41, 10, v41
	v_lshlrev_b32_e32 v42, 10, v42
	v_lshlrev_b32_e32 v43, 10, v43
	v_lshlrev_b32_e32 v44, 10, v44
	v_lshlrev_b32_e32 v45, 10, v45
	v_lshlrev_b32_e32 v46, 10, v46
	v_lshlrev_b32_e32 v47, 10, v47
	v_lshlrev_b32_e32 v48, 10, v48
	v_lshlrev_b32_e32 v49, 10, v49
	v_lshlrev_b32_e32 v50, 10, v50
	v_lshlrev_b32_e32 v51, 10, v51
	v_lshlrev_b32_e32 v52, 10, v52
	v_lshlrev_b32_e32 v53, 10, v53
	v_lshlrev_b32_e32 v54, 10, v19
	v_add_u32_e32 v55, v70, v18
	v_add_u32_e32 v56, v70, v32
	v_add_u32_e32 v57, v70, v57
	v_add_u32_e32 v58, v70, v58
	v_add_u32_e32 v59, v70, v59
	v_add_u32_e32 v60, v70, v60
	v_add_u32_e32 v61, v70, v61
	v_add_u32_e32 v62, v70, v62
	v_add_u32_e32 v63, v70, v63
	v_add_u32_e32 v64, v70, v64
	v_add_u32_e32 v65, v70, v65
	v_add_u32_e32 v66, v70, v66
	v_add_u32_e32 v67, v70, v67
	v_add_u32_e32 v68, v70, v68
	v_add_u32_e32 v69, v70, v69
	v_add_u32_e32 v70, v70, v71
	v_readlane_b32 s12, v253, 4
	v_readlane_b32 s13, v253, 5
	v_readlane_b32 s14, v253, 6
	v_readlane_b32 s15, v253, 7
	v_readlane_b32 s16, v253, 8
	v_readlane_b32 s17, v253, 9
	v_readlane_b32 s18, v253, 10
	v_readlane_b32 s19, v253, 11
	v_readlane_b32 s20, v253, 12
	v_readlane_b32 s21, v253, 13
	v_readlane_b32 s22, v253, 14
	v_readlane_b32 s23, v253, 15
	s_branch .LBB0_240
